# PLE-gate GEMM epilogue: load both halves of each row group's pp tile together (8 fewer serialized round trips per tile)
# speedup vs baseline: 1.0057x; 1.0057x over previous
; #define PG8_STAGE(bufoff, gbase, voff) do { _Pragma("unroll") for (int _i = 0; _i < 2; ++_i) \
;         __builtin_amdgcn_global_load_lds((const unsigned*)((const char*)(gbase) + (voff)[_i]), (LAS unsigned*)(lds + (bufoff) + ldsw + _i * 8192), 16, 0, 0); } while (0)
; #define PG8_LDA(dst, b, h) do { _Pragma("unroll") for (int m = 0; m < 4; ++m) _Pragma("unroll") for (int k = 0; k < 2; ++k) dst[m][k] = *(const LAS bf16x8*)(lds + PG8_SA(b, h) + aoff + m * 2048 + k * 1024); } while (0)
; #define PG8_LDB(dst, b, h) do { _Pragma("unroll") for (int n = 0; n < 2; ++n) _Pragma("unroll") for (int k = 0; k < 2; ++k) dst[n][k] = *(const LAS bf16x8*)(lds + PG8_SB(b, h) + boff + n * 2048 + k * 1024); } while (0)
; #define PG8_MMA(ai, bj, At, Bt) do { __builtin_amdgcn_s_setprio(1); _Pragma("unroll") for (int m = 0; m < 4; ++m) _Pragma("unroll") for (int n = 0; n < 2; ++n) _Pragma("unroll") for (int k = 0; k < 2; ++k) \
;         acc[ai][bj][m][n] = __builtin_amdgcn_mfma_f32_16x16x32_bf16(Bt[n][k], At[m][k], acc[ai][bj][m][n], 0, 0, 0); __builtin_amdgcn_s_setprio(0); } while (0)
; #define PG8_WAIT_V(n) asm volatile("s_waitcnt vmcnt(" #n ")" ::: "memory")
; #define PG8_WAIT_L(n) asm volatile("s_waitcnt lgkmcnt(" #n ")" ::: "memory")
; #define PG8_BAR __builtin_amdgcn_s_barrier()
; #define PG8_SCHED __builtin_amdgcn_sched_barrier(0)
; template <class Epi>
; __device__ __forceinline__ void gemm_phase(LAS unsigned char* lds, const Gemm g, const StaticOrder& S, const Epi& E) {
;     ...
;             PG8_LDB(B0, 0, 0); PG8_SCHED; PG8_LDA(At, 0, 0); PG8_STAGE(PG8_SA(1, 1), a1 + hstep, voffA);
;             PG8_WAIT_L(8); PG8_BAR; PG8_WAIT_L(0); PG8_MMA(0, 0, At, B0); PG8_BAR; PG8_SCHED;
;             PG8_LDB(B1, 0, 1); PG8_STAGE(PG8_SB(0, 0), b2, voffB);
;             PG8_BAR; PG8_WAIT_L(0); PG8_MMA(0, 1, At, B1); PG8_BAR;
;             PG8_LDA(At, 0, 1); PG8_STAGE(PG8_SA(0, 0), a2, voffA);
;             PG8_BAR; PG8_WAIT_L(0); PG8_MMA(1, 0, At, B0); PG8_BAR; PG8_SCHED;
;             PG8_STAGE(PG8_SB(0, 1), b2 + hstep, voffB);
;             PG8_WAIT_V(6); PG8_BAR; PG8_MMA(1, 1, At, B1); PG8_BAR;
.LBB0_999:
	ds_read_b128 v[140:143], v151
	ds_read_b128 v[144:147], v151 offset:1024
	ds_read_b128 v[154:157], v151 offset:2048
	ds_read_b128 v[160:163], v151 offset:3072
	s_add_u32 s48, s46, 0xfff80080
	s_addc_u32 s49, s47, -1
	s_cmp_eq_u32 s63, 28
	s_cselect_b32 s51, s37, s49
	s_cselect_b32 s50, s59, s48
	s_cselect_b32 s49, s35, s62
	s_cselect_b32 s48, s60, s61
	s_add_i32 m0, s28, 0xc000
	ds_read_b128 v[164:167], v152
	ds_read_b128 v[168:171], v152 offset:1024
	ds_read_b128 v[172:175], v152 offset:2048
	ds_read_b128 v[176:179], v152 offset:3072
	ds_read_b128 v[180:183], v152 offset:4096
	ds_read_b128 v[184:187], v152 offset:5120
	ds_read_b128 v[188:191], v152 offset:6144
	ds_read_b128 v[192:195], v152 offset:7168
	global_load_lds_dwordx4 v136, s[46:47]
	s_add_i32 m0, s28, 0xe000
	s_nop 0
	global_load_lds_dwordx4 v138, s[46:47]
	s_waitcnt lgkmcnt(8)
	s_barrier
	s_waitcnt lgkmcnt(0)
	s_setprio 1
	s_waitcnt lgkmcnt(0)
	v_mfma_f32_16x16x32_bf16 v[124:127], v[140:143], v[164:167], v[124:127]
	v_mfma_f32_16x16x32_bf16 v[120:123], v[154:157], v[164:167], v[120:123]
	v_mfma_f32_16x16x32_bf16 v[108:111], v[140:143], v[172:175], v[108:111]
	v_mfma_f32_16x16x32_bf16 v[104:107], v[154:157], v[172:175], v[104:107]
	v_mfma_f32_16x16x32_bf16 v[92:95], v[140:143], v[180:183], v[92:95]
	v_mfma_f32_16x16x32_bf16 v[88:91], v[154:157], v[180:183], v[88:91]
	v_mfma_f32_16x16x32_bf16 v[76:79], v[140:143], v[188:191], v[76:79]
	v_mfma_f32_16x16x32_bf16 v[72:75], v[154:157], v[188:191], v[72:75]
	v_mfma_f32_16x16x32_bf16 v[124:127], v[144:147], v[168:171], v[124:127]
	v_mfma_f32_16x16x32_bf16 v[120:123], v[160:163], v[168:171], v[120:123]
	v_mfma_f32_16x16x32_bf16 v[108:111], v[144:147], v[176:179], v[108:111]
	v_mfma_f32_16x16x32_bf16 v[104:107], v[160:163], v[176:179], v[104:107]
	v_mfma_f32_16x16x32_bf16 v[92:95], v[144:147], v[184:187], v[92:95]
	v_mfma_f32_16x16x32_bf16 v[88:91], v[160:163], v[184:187], v[88:91]
	v_mfma_f32_16x16x32_bf16 v[76:79], v[144:147], v[192:195], v[76:79]
	v_mfma_f32_16x16x32_bf16 v[72:75], v[160:163], v[192:195], v[72:75]
	s_setprio 0
	s_barrier
	s_add_i32 s64, s56, s23
	s_add_u32 s98, s48, s4
	s_addc_u32 s99, s49, s5
	s_mov_b32 m0, s64
	ds_read_b128 v[196:199], v153
	ds_read_b128 v[200:203], v153 offset:1024
	ds_read_b128 v[204:207], v153 offset:2048
	ds_read_b128 v[208:211], v153 offset:3072
	global_load_lds_dwordx4 v132, s[48:49]
	s_add_i32 m0, s64, 0x2000
	s_nop 0
	global_load_lds_dwordx4 v128, s[48:49]
	s_barrier
	s_waitcnt lgkmcnt(0)
	s_setprio 1
	s_waitcnt lgkmcnt(0)
	v_mfma_f32_16x16x32_bf16 v[116:119], v[196:199], v[164:167], v[116:119]
	v_mfma_f32_16x16x32_bf16 v[112:115], v[204:207], v[164:167], v[112:115]
	v_mfma_f32_16x16x32_bf16 v[100:103], v[196:199], v[172:175], v[100:103]
	v_mfma_f32_16x16x32_bf16 v[96:99], v[204:207], v[172:175], v[96:99]
	v_mfma_f32_16x16x32_bf16 v[84:87], v[196:199], v[180:183], v[84:87]
	v_mfma_f32_16x16x32_bf16 v[80:83], v[204:207], v[180:183], v[80:83]
	v_mfma_f32_16x16x32_bf16 v[68:71], v[196:199], v[188:191], v[68:71]
	v_mfma_f32_16x16x32_bf16 v[64:67], v[204:207], v[188:191], v[64:67]
	v_mfma_f32_16x16x32_bf16 v[116:119], v[200:203], v[168:171], v[116:119]
	v_mfma_f32_16x16x32_bf16 v[112:115], v[208:211], v[168:171], v[112:115]
	v_mfma_f32_16x16x32_bf16 v[100:103], v[200:203], v[176:179], v[100:103]
	v_mfma_f32_16x16x32_bf16 v[96:99], v[208:211], v[176:179], v[96:99]
	v_mfma_f32_16x16x32_bf16 v[84:87], v[200:203], v[184:187], v[84:87]
	v_mfma_f32_16x16x32_bf16 v[80:83], v[208:211], v[184:187], v[80:83]
	v_mfma_f32_16x16x32_bf16 v[68:71], v[200:203], v[192:195], v[68:71]
	v_mfma_f32_16x16x32_bf16 v[64:67], v[208:211], v[192:195], v[64:67]
	s_setprio 0
	s_mov_b32 m0, s28
	s_add_u32 s100, s50, s4
	s_addc_u32 s101, s51, s5
	s_barrier
	ds_read_b128 v[164:167], v152 offset:16384
	ds_read_b128 v[168:171], v152 offset:17408
	ds_read_b128 v[172:175], v152 offset:18432
	ds_read_b128 v[176:179], v152 offset:19456
	ds_read_b128 v[180:183], v152 offset:20480
	ds_read_b128 v[184:187], v152 offset:21504
	ds_read_b128 v[188:191], v152 offset:22528
	ds_read_b128 v[192:195], v152 offset:23552
	global_load_lds_dwordx4 v134, s[50:51]
	s_mov_b32 m0, s29
	s_nop 0
	global_load_lds_dwordx4 v130, s[50:51]
	s_barrier
	s_waitcnt lgkmcnt(0)
	s_setprio 1
	s_waitcnt lgkmcnt(0)
	v_mfma_f32_16x16x32_bf16 v[60:63], v[140:143], v[164:167], v[60:63]
	v_mfma_f32_16x16x32_bf16 v[56:59], v[154:157], v[164:167], v[56:59]
	v_mfma_f32_16x16x32_bf16 v[44:47], v[140:143], v[172:175], v[44:47]
	v_mfma_f32_16x16x32_bf16 v[40:43], v[154:157], v[172:175], v[40:43]
	v_mfma_f32_16x16x32_bf16 v[28:31], v[140:143], v[180:183], v[28:31]
	v_mfma_f32_16x16x32_bf16 v[24:27], v[154:157], v[180:183], v[24:27]
	v_mfma_f32_16x16x32_bf16 v[12:15], v[140:143], v[188:191], v[12:15]
	v_mfma_f32_16x16x32_bf16 v[8:11], v[154:157], v[188:191], v[8:11]
	v_mfma_f32_16x16x32_bf16 v[60:63], v[144:147], v[168:171], v[60:63]
	v_mfma_f32_16x16x32_bf16 v[56:59], v[160:163], v[168:171], v[56:59]
	v_mfma_f32_16x16x32_bf16 v[44:47], v[144:147], v[176:179], v[44:47]
	v_mfma_f32_16x16x32_bf16 v[40:43], v[160:163], v[176:179], v[40:43]
	v_mfma_f32_16x16x32_bf16 v[28:31], v[144:147], v[184:187], v[28:31]
	v_mfma_f32_16x16x32_bf16 v[24:27], v[160:163], v[184:187], v[24:27]
	v_mfma_f32_16x16x32_bf16 v[12:15], v[144:147], v[192:195], v[12:15]
	v_mfma_f32_16x16x32_bf16 v[8:11], v[160:163], v[192:195], v[8:11]
	s_setprio 0
	s_barrier
	s_add_u32 s64, s48, 0x80000
	s_addc_u32 s65, s49, 0
	s_add_i32 s66, s57, s23
	s_mov_b32 m0, s66
	s_nop 0
	global_load_lds_dwordx4 v132, s[64:65]
	s_add_i32 m0, s66, 0x2000
	s_nop 0
	global_load_lds_dwordx4 v128, s[64:65]
	s_waitcnt vmcnt(6)
	s_barrier
; #define PG8_STAGE(bufoff, gbase, voff) do { _Pragma("unroll") for (int _i = 0; _i < 2; ++_i) \
;         __builtin_amdgcn_global_load_lds((const unsigned*)((const char*)(gbase) + (voff)[_i]), (LAS unsigned*)(lds + (bufoff) + ldsw + _i * 8192), 16, 0, 0); } while (0)
; #define PG8_LDA(dst, b, h) do { _Pragma("unroll") for (int m = 0; m < 4; ++m) _Pragma("unroll") for (int k = 0; k < 2; ++k) dst[m][k] = *(const LAS bf16x8*)(lds + PG8_SA(b, h) + aoff + m * 2048 + k * 1024); } while (0)
; #define PG8_LDB(dst, b, h) do { _Pragma("unroll") for (int n = 0; n < 2; ++n) _Pragma("unroll") for (int k = 0; k < 2; ++k) dst[n][k] = *(const LAS bf16x8*)(lds + PG8_SB(b, h) + boff + n * 2048 + k * 1024); } while (0)
; #define PG8_MMA(ai, bj, At, Bt) do { __builtin_amdgcn_s_setprio(1); _Pragma("unroll") for (int m = 0; m < 4; ++m) _Pragma("unroll") for (int n = 0; n < 2; ++n) _Pragma("unroll") for (int k = 0; k < 2; ++k) \
;         acc[ai][bj][m][n] = __builtin_amdgcn_mfma_f32_16x16x32_bf16(Bt[n][k], At[m][k], acc[ai][bj][m][n], 0, 0, 0); __builtin_amdgcn_s_setprio(0); } while (0)
; #define PG8_WAIT_V(n) asm volatile("s_waitcnt vmcnt(" #n ")" ::: "memory")
; #define PG8_WAIT_L(n) asm volatile("s_waitcnt lgkmcnt(" #n ")" ::: "memory")
; #define PG8_BAR __builtin_amdgcn_s_barrier()
; #define PG8_SCHED __builtin_amdgcn_sched_barrier(0)
; template <class Epi>
; __device__ __forceinline__ void gemm_phase(LAS unsigned char* lds, const Gemm g, const StaticOrder& S, const Epi& E) {
;     ...
;             PG8_WAIT_V(6); PG8_BAR; PG8_MMA(1, 1, At, B1); PG8_BAR;
;             PG8_LDB(B0, 1, 0); PG8_SCHED; PG8_LDA(At, 1, 0); PG8_STAGE(PG8_SA(0, 1), a2 + hstep, voffA);
;             PG8_WAIT_L(8); PG8_BAR; PG8_WAIT_L(0); PG8_MMA(0, 0, At, B0); PG8_BAR; PG8_SCHED;
;             PG8_LDB(B1, 1, 1); PG8_STAGE(PG8_SB(1, 0), b3, voffB);
;             PG8_BAR; PG8_WAIT_L(0); PG8_MMA(0, 1, At, B1); PG8_BAR;
;             PG8_LDA(At, 1, 1); PG8_STAGE(PG8_SA(1, 0), a3, voffA);
	s_setprio 1
	v_mfma_f32_16x16x32_bf16 v[52:55], v[196:199], v[164:167], v[52:55]
	v_mfma_f32_16x16x32_bf16 v[48:51], v[204:207], v[164:167], v[48:51]
	v_mfma_f32_16x16x32_bf16 v[36:39], v[196:199], v[172:175], v[36:39]
	v_mfma_f32_16x16x32_bf16 v[32:35], v[204:207], v[172:175], v[32:35]
	v_mfma_f32_16x16x32_bf16 v[20:23], v[196:199], v[180:183], v[20:23]
	v_mfma_f32_16x16x32_bf16 v[16:19], v[204:207], v[180:183], v[16:19]
	v_mfma_f32_16x16x32_bf16 v[4:7], v[196:199], v[188:191], v[4:7]
	v_mfma_f32_16x16x32_bf16 v[0:3], v[204:207], v[188:191], v[0:3]
	v_mfma_f32_16x16x32_bf16 v[52:55], v[200:203], v[168:171], v[52:55]
	v_mfma_f32_16x16x32_bf16 v[48:51], v[208:211], v[168:171], v[48:51]
	v_mfma_f32_16x16x32_bf16 v[36:39], v[200:203], v[176:179], v[36:39]
	v_mfma_f32_16x16x32_bf16 v[32:35], v[208:211], v[176:179], v[32:35]
	v_mfma_f32_16x16x32_bf16 v[20:23], v[200:203], v[184:187], v[20:23]
	v_mfma_f32_16x16x32_bf16 v[16:19], v[208:211], v[184:187], v[16:19]
	v_mfma_f32_16x16x32_bf16 v[4:7], v[200:203], v[192:195], v[4:7]
	v_mfma_f32_16x16x32_bf16 v[0:3], v[208:211], v[192:195], v[0:3]
	s_setprio 0
	s_add_i32 s64, 0, 0x18000
	v_add_u32_e32 v160, s64, v149
	s_barrier
	ds_read_b128 v[140:143], v160
	ds_read_b128 v[144:147], v160 offset:1024
	ds_read_b128 v[154:157], v160 offset:2048
	ds_read_b128 v[160:163], v160 offset:3072
	s_add_u32 s50, s50, 0x80000
	s_addc_u32 s51, s51, 0
	s_mov_b32 m0, s33
	ds_read_b128 v[164:167], v152 offset:32768
	ds_read_b128 v[168:171], v152 offset:33792
	ds_read_b128 v[172:175], v152 offset:34816
	ds_read_b128 v[176:179], v152 offset:35840
	ds_read_b128 v[180:183], v152 offset:36864
	ds_read_b128 v[184:187], v152 offset:37888
	ds_read_b128 v[188:191], v152 offset:38912
	ds_read_b128 v[192:195], v152 offset:39936
	global_load_lds_dwordx4 v134, s[50:51]
	s_mov_b32 m0, s45
	s_nop 0
	global_load_lds_dwordx4 v130, s[50:51]
	s_waitcnt lgkmcnt(8)
	s_barrier
	s_waitcnt lgkmcnt(0)
	s_setprio 1
	s_waitcnt lgkmcnt(0)
	v_mfma_f32_16x16x32_bf16 v[124:127], v[140:143], v[164:167], v[124:127]
	v_mfma_f32_16x16x32_bf16 v[120:123], v[154:157], v[164:167], v[120:123]
	v_mfma_f32_16x16x32_bf16 v[108:111], v[140:143], v[172:175], v[108:111]
	v_mfma_f32_16x16x32_bf16 v[104:107], v[154:157], v[172:175], v[104:107]
	v_mfma_f32_16x16x32_bf16 v[92:95], v[140:143], v[180:183], v[92:95]
	v_mfma_f32_16x16x32_bf16 v[88:91], v[154:157], v[180:183], v[88:91]
	v_mfma_f32_16x16x32_bf16 v[76:79], v[140:143], v[188:191], v[76:79]
	v_mfma_f32_16x16x32_bf16 v[72:75], v[154:157], v[188:191], v[72:75]
	v_mfma_f32_16x16x32_bf16 v[124:127], v[144:147], v[168:171], v[124:127]
	v_mfma_f32_16x16x32_bf16 v[120:123], v[160:163], v[168:171], v[120:123]
	v_mfma_f32_16x16x32_bf16 v[108:111], v[144:147], v[176:179], v[108:111]
	v_mfma_f32_16x16x32_bf16 v[104:107], v[160:163], v[176:179], v[104:107]
	v_mfma_f32_16x16x32_bf16 v[92:95], v[144:147], v[184:187], v[92:95]
	v_mfma_f32_16x16x32_bf16 v[88:91], v[160:163], v[184:187], v[88:91]
	v_mfma_f32_16x16x32_bf16 v[76:79], v[144:147], v[192:195], v[76:79]
	v_mfma_f32_16x16x32_bf16 v[72:75], v[160:163], v[192:195], v[72:75]
	s_setprio 0
	s_barrier
	s_add_i32 s50, 0, 0x1c000
	s_add_i32 s51, s64, s23
	v_add_u32_e32 v208, s50, v149
	s_mov_b32 m0, s51
	ds_read_b128 v[196:199], v208
	ds_read_b128 v[200:203], v208 offset:1024
	ds_read_b128 v[204:207], v208 offset:2048
	ds_read_b128 v[208:211], v208 offset:3072
	global_load_lds_dwordx4 v132, s[98:99]
	s_add_i32 m0, s51, 0x2000
	s_nop 0
	global_load_lds_dwordx4 v128, s[98:99]
	s_barrier
	s_waitcnt lgkmcnt(0)
	s_setprio 1
	s_waitcnt lgkmcnt(0)
	v_mfma_f32_16x16x32_bf16 v[116:119], v[196:199], v[164:167], v[116:119]
	v_mfma_f32_16x16x32_bf16 v[112:115], v[204:207], v[164:167], v[112:115]
	v_mfma_f32_16x16x32_bf16 v[100:103], v[196:199], v[172:175], v[100:103]
	v_mfma_f32_16x16x32_bf16 v[96:99], v[204:207], v[172:175], v[96:99]
	v_mfma_f32_16x16x32_bf16 v[84:87], v[196:199], v[180:183], v[84:87]
	v_mfma_f32_16x16x32_bf16 v[80:83], v[204:207], v[180:183], v[80:83]
	v_mfma_f32_16x16x32_bf16 v[68:71], v[196:199], v[188:191], v[68:71]
	v_mfma_f32_16x16x32_bf16 v[64:67], v[204:207], v[188:191], v[64:67]
	v_mfma_f32_16x16x32_bf16 v[116:119], v[200:203], v[168:171], v[116:119]
	v_mfma_f32_16x16x32_bf16 v[112:115], v[208:211], v[168:171], v[112:115]
	v_mfma_f32_16x16x32_bf16 v[100:103], v[200:203], v[176:179], v[100:103]
	v_mfma_f32_16x16x32_bf16 v[96:99], v[208:211], v[176:179], v[96:99]
	v_mfma_f32_16x16x32_bf16 v[84:87], v[200:203], v[184:187], v[84:87]
	v_mfma_f32_16x16x32_bf16 v[80:83], v[208:211], v[184:187], v[80:83]
	v_mfma_f32_16x16x32_bf16 v[68:71], v[200:203], v[192:195], v[68:71]
	v_mfma_f32_16x16x32_bf16 v[64:67], v[208:211], v[192:195], v[64:67]
	s_setprio 0
	s_mov_b32 m0, s53
	s_barrier
	ds_read_b128 v[164:167], v152 offset:49152
	ds_read_b128 v[168:171], v152 offset:50176
	ds_read_b128 v[172:175], v152 offset:51200
	ds_read_b128 v[176:179], v152 offset:52224
	ds_read_b128 v[180:183], v152 offset:53248
	ds_read_b128 v[184:187], v152 offset:54272
	ds_read_b128 v[188:191], v152 offset:55296
	ds_read_b128 v[192:195], v152 offset:56320
	global_load_lds_dwordx4 v134, s[100:101]
	s_mov_b32 m0, s54
	s_nop 0
	global_load_lds_dwordx4 v130, s[100:101]
	s_barrier
; __device__ __forceinline__ float bf_lo(unsigned w) { return __uint_as_float(w << 16); }
; __device__ __forceinline__ float bf_hi(unsigned w) { return __uint_as_float(w & 0xffff0000u); }
; __device__ __forceinline__ float fast_rcp(float x) { return __builtin_amdgcn_rcpf(x); }
; __device__ __forceinline__ float fast_exp2(float x) { return __builtin_amdgcn_exp2f(x); }
; #define PG8_STAGE(bufoff, gbase, voff) do { _Pragma("unroll") for (int _i = 0; _i < 2; ++_i) \
;         __builtin_amdgcn_global_load_lds((const unsigned*)((const char*)(gbase) + (voff)[_i]), (LAS unsigned*)(lds + (bufoff) + ldsw + _i * 8192), 16, 0, 0); } while (0)
; #define PG8_MMA(ai, bj, At, Bt) do { __builtin_amdgcn_s_setprio(1); _Pragma("unroll") for (int m = 0; m < 4; ++m) _Pragma("unroll") for (int n = 0; n < 2; ++n) _Pragma("unroll") for (int k = 0; k < 2; ++k) \
;         acc[ai][bj][m][n] = __builtin_amdgcn_mfma_f32_16x16x32_bf16(Bt[n][k], At[m][k], acc[ai][bj][m][n], 0, 0, 0); __builtin_amdgcn_s_setprio(0); } while (0)
; #define PG8_BAR __builtin_amdgcn_s_barrier()
; template <class Epi>
; __device__ __forceinline__ void gemm_phase(LAS unsigned char* lds, const Gemm g, const StaticOrder& S, const Epi& E) {
;     ...
;             PG8_BAR; PG8_WAIT_L(0); PG8_MMA(1, 0, At, B0); PG8_BAR; PG8_SCHED;
;             PG8_STAGE(PG8_SB(1, 1), b3 + hstep, voffB);
;             PG8_WAIT_V(6); PG8_BAR; PG8_MMA(1, 1, At, B1); PG8_BAR;
;     __device__ __forceinline__ void operator()(const f32x4 (&acc)[2][2][4][2], const Unit& u, int wr, int wc, int fr, int fq) const {
;     ...
;             for (int m = 0; m < 4; ++m) { const size_t ro = (size_t)(row0 + ai * HALF + m * 16) * DM + col0; const float nr = -LOG2E * rs[row0 + ai * HALF + m * 16];
; #pragma unroll
;                 for (int bj = 0; bj < 2; ++bj) {
;                     const u32x4 pw = *(const u32x4*)(PP + ro + bj * HALF);
;                     const float pv[8] = {bf_lo(pw.x), bf_hi(pw.x), bf_lo(pw.y), bf_hi(pw.y), bf_lo(pw.z), bf_hi(pw.z), bf_lo(pw.w), bf_hi(pw.w)};
;                     f32x4 t0, t1;
; #pragma unroll
;                     for (int j = 0; j < 4; ++j) {
;                         t0[j] = fast_rcp(1.0f + fast_exp2(acc[ai][bj][m][0][j] * nr)) * pv[j];
;                         t1[j] = fast_rcp(1.0f + fast_exp2(acc[ai][bj][m][1][j] * nr)) * pv[4 + j]; }
;                     *(u32x4*)(O + ro + bj * HALF) = pack8(t0, t1); } }
	s_waitcnt lgkmcnt(0)
	s_setprio 1
	s_waitcnt lgkmcnt(0)
	v_mfma_f32_16x16x32_bf16 v[60:63], v[140:143], v[164:167], v[60:63]
	v_mfma_f32_16x16x32_bf16 v[56:59], v[154:157], v[164:167], v[56:59]
	v_mfma_f32_16x16x32_bf16 v[44:47], v[140:143], v[172:175], v[44:47]
	v_mfma_f32_16x16x32_bf16 v[40:43], v[154:157], v[172:175], v[40:43]
	v_mfma_f32_16x16x32_bf16 v[28:31], v[140:143], v[180:183], v[28:31]
	v_mfma_f32_16x16x32_bf16 v[24:27], v[154:157], v[180:183], v[24:27]
	v_mfma_f32_16x16x32_bf16 v[12:15], v[140:143], v[188:191], v[12:15]
	v_mfma_f32_16x16x32_bf16 v[8:11], v[154:157], v[188:191], v[8:11]
	v_mfma_f32_16x16x32_bf16 v[60:63], v[144:147], v[168:171], v[60:63]
	v_mfma_f32_16x16x32_bf16 v[56:59], v[160:163], v[168:171], v[56:59]
	v_mfma_f32_16x16x32_bf16 v[44:47], v[144:147], v[176:179], v[44:47]
	v_mfma_f32_16x16x32_bf16 v[40:43], v[160:163], v[176:179], v[40:43]
	v_mfma_f32_16x16x32_bf16 v[28:31], v[144:147], v[184:187], v[28:31]
	v_mfma_f32_16x16x32_bf16 v[24:27], v[160:163], v[184:187], v[24:27]
	v_mfma_f32_16x16x32_bf16 v[12:15], v[144:147], v[192:195], v[12:15]
	v_mfma_f32_16x16x32_bf16 v[8:11], v[160:163], v[192:195], v[8:11]
	s_setprio 0
	s_barrier
	s_add_u32 s48, s48, 0x80080
	s_addc_u32 s49, s49, 0
	s_add_i32 s50, s50, s23
	s_mov_b32 m0, s50
	s_nop 0
	global_load_lds_dwordx4 v132, s[48:49]
	s_add_i32 m0, s50, 0x2000
	s_nop 0
	global_load_lds_dwordx4 v128, s[48:49]
	s_waitcnt vmcnt(6)
	s_barrier
	s_setprio 1
	v_mfma_f32_16x16x32_bf16 v[52:55], v[196:199], v[164:167], v[52:55]
	v_mfma_f32_16x16x32_bf16 v[48:51], v[204:207], v[164:167], v[48:51]
	v_mfma_f32_16x16x32_bf16 v[36:39], v[196:199], v[172:175], v[36:39]
	v_mfma_f32_16x16x32_bf16 v[32:35], v[204:207], v[172:175], v[32:35]
	v_mfma_f32_16x16x32_bf16 v[20:23], v[196:199], v[180:183], v[20:23]
	v_mfma_f32_16x16x32_bf16 v[16:19], v[204:207], v[180:183], v[16:19]
	v_mfma_f32_16x16x32_bf16 v[4:7], v[196:199], v[188:191], v[4:7]
	v_mfma_f32_16x16x32_bf16 v[0:3], v[204:207], v[188:191], v[0:3]
	v_mfma_f32_16x16x32_bf16 v[52:55], v[200:203], v[168:171], v[52:55]
	v_mfma_f32_16x16x32_bf16 v[48:51], v[208:211], v[168:171], v[48:51]
	v_mfma_f32_16x16x32_bf16 v[36:39], v[200:203], v[176:179], v[36:39]
	v_mfma_f32_16x16x32_bf16 v[32:35], v[208:211], v[176:179], v[32:35]
	v_mfma_f32_16x16x32_bf16 v[20:23], v[200:203], v[184:187], v[20:23]
	v_mfma_f32_16x16x32_bf16 v[16:19], v[208:211], v[184:187], v[16:19]
	v_mfma_f32_16x16x32_bf16 v[4:7], v[200:203], v[192:195], v[4:7]
	v_mfma_f32_16x16x32_bf16 v[0:3], v[208:211], v[192:195], v[0:3]
	s_setprio 0
	s_add_i32 s63, s63, 2
	s_add_u32 s46, s46, 0x100
	s_addc_u32 s47, s47, 0
	s_add_u32 s61, s61, 0x100
	s_addc_u32 s62, s62, 0
	s_cmp_gt_u32 s63, 29
	s_barrier
	s_cbranch_scc0 .LBB0_999
	v_lshl_add_u32 v144, s44, 8, v148
	v_ashrrev_i32_e32 v145, 31, v144
	v_lshl_add_u64 v[140:141], v[144:145], 2, s[14:15]
	global_load_dword v164, v[140:141], off
	v_lshl_or_b32 v146, s58, 8, v150
	v_ashrrev_i32_e32 v147, 31, v146
	v_lshlrev_b64 v[142:143], 11, v[144:145]
	v_lshl_add_u64 v[142:143], v[142:143], 0, v[146:147]
	v_lshlrev_b64 v[142:143], 1, v[142:143]
	v_lshl_add_u64 v[160:161], s[20:21], 0, v[142:143]
	global_load_dwordx4 v[154:157], v[160:161], off
	global_load_dwordx4 v[220:223], v[160:161], off offset:256
	v_lshl_add_u64 v[162:163], s[24:25], 0, v[142:143]
	s_and_b64 vcc, exec, s[38:39]
	s_mov_b32 s58, s34
	s_mov_b32 s44, s36
	s_mov_b64 s[48:49], s[42:43]
	s_mov_b64 s[46:47], s[40:41]
	s_waitcnt vmcnt(0)
	v_mul_f32_e32 v145, 0xbfb8aa3b, v164
	v_mul_f32_e32 v124, v124, v145
	v_mul_f32_e32 v120, v120, v145
	v_mul_f32_e32 v125, v125, v145
	v_mul_f32_e32 v121, v121, v145
	v_mul_f32_e32 v126, v126, v145
	v_mul_f32_e32 v122, v122, v145
	v_mul_f32_e32 v127, v127, v145
	v_mul_f32_e32 v123, v123, v145
	v_exp_f32_e32 v124, v124
	v_exp_f32_e32 v120, v120
	v_exp_f32_e32 v125, v125
	v_exp_f32_e32 v121, v121
	v_exp_f32_e32 v126, v126
	v_exp_f32_e32 v122, v122
	v_exp_f32_e32 v127, v127
	v_exp_f32_e32 v123, v123
	v_add_f32_e32 v124, 1.0, v124
	v_add_f32_e32 v120, 1.0, v120
	v_add_f32_e32 v125, 1.0, v125
	v_add_f32_e32 v121, 1.0, v121
	v_add_f32_e32 v126, 1.0, v126
	v_add_f32_e32 v122, 1.0, v122
	v_add_f32_e32 v127, 1.0, v127
	v_add_f32_e32 v123, 1.0, v123
	v_rcp_f32_e32 v124, v124
	v_rcp_f32_e32 v120, v120
	v_rcp_f32_e32 v125, v125
	v_rcp_f32_e32 v121, v121
	v_rcp_f32_e32 v126, v126
	v_rcp_f32_e32 v122, v122
	v_rcp_f32_e32 v127, v127
	v_rcp_f32_e32 v123, v123
	v_lshlrev_b32_e32 v164, 16, v154
	v_and_b32_e32 v154, 0xffff0000, v154
	v_lshlrev_b32_e32 v165, 16, v155
	v_and_b32_e32 v155, 0xffff0000, v155
	v_lshlrev_b32_e32 v166, 16, v156
	v_and_b32_e32 v156, 0xffff0000, v156
	v_lshlrev_b32_e32 v167, 16, v157
	v_and_b32_e32 v157, 0xffff0000, v157
	v_mul_f32_e32 v124, v124, v164
	v_mul_f32_e32 v164, v120, v166
	v_mul_f32_e32 v120, v125, v154
	v_mul_f32_e32 v125, v121, v156
	v_mul_f32_e32 v121, v126, v165
	v_mul_f32_e32 v126, v122, v167
	v_mul_f32_e32 v122, v127, v155
	v_mul_f32_e32 v123, v123, v157
	v_cvt_pk_bf16_f32 v120, v124, v120
	v_cvt_pk_bf16_f32 v121, v121, v122
	v_cvt_pk_bf16_f32 v122, v164, v125
	v_cvt_pk_bf16_f32 v123, v126, v123
	global_store_dwordx4 v[162:163], v[120:123], off
	v_mul_f32_e32 v116, v116, v145
	v_mul_f32_e32 v112, v112, v145
	v_mul_f32_e32 v117, v117, v145
	v_mul_f32_e32 v113, v113, v145
	v_mul_f32_e32 v118, v118, v145
	v_mul_f32_e32 v114, v114, v145
	v_mul_f32_e32 v119, v119, v145
	v_mul_f32_e32 v115, v115, v145
	v_exp_f32_e32 v116, v116
	v_exp_f32_e32 v112, v112
	v_exp_f32_e32 v117, v117
	v_exp_f32_e32 v113, v113
	v_exp_f32_e32 v118, v118
	v_exp_f32_e32 v114, v114
	v_exp_f32_e32 v119, v119
	v_exp_f32_e32 v115, v115
	v_add_f32_e32 v116, 1.0, v116
; __device__ __forceinline__ float bf_lo(unsigned w) { return __uint_as_float(w << 16); }
; __device__ __forceinline__ float bf_hi(unsigned w) { return __uint_as_float(w & 0xffff0000u); }
; __device__ __forceinline__ float fast_rcp(float x) { return __builtin_amdgcn_rcpf(x); }
; __device__ __forceinline__ float fast_exp2(float x) { return __builtin_amdgcn_exp2f(x); }
; __device__ __forceinline__ u32x4 pack8(f32x4 v0, f32x4 v1) { u32x4 w; w.x = cvt_pk_bf16(v0[0], v0[1]); w.y = cvt_pk_bf16(v0[2], v0[3]); w.z = cvt_pk_bf16(v1[0], v1[1]); w.w = cvt_pk_bf16(v1[2], v1[3]); return w; }
;     __device__ __forceinline__ void operator()(const f32x4 (&acc)[2][2][4][2], const Unit& u, int wr, int wc, int fr, int fq) const {
;     ...
;             for (int m = 0; m < 4; ++m) { const size_t ro = (size_t)(row0 + ai * HALF + m * 16) * DM + col0; const float nr = -LOG2E * rs[row0 + ai * HALF + m * 16];
; #pragma unroll
;                 for (int bj = 0; bj < 2; ++bj) {
;                     const u32x4 pw = *(const u32x4*)(PP + ro + bj * HALF);
;                     const float pv[8] = {bf_lo(pw.x), bf_hi(pw.x), bf_lo(pw.y), bf_hi(pw.y), bf_lo(pw.z), bf_hi(pw.z), bf_lo(pw.w), bf_hi(pw.w)};
;                     f32x4 t0, t1;
; #pragma unroll
;                     for (int j = 0; j < 4; ++j) {
;                         t0[j] = fast_rcp(1.0f + fast_exp2(acc[ai][bj][m][0][j] * nr)) * pv[j];
;                         t1[j] = fast_rcp(1.0f + fast_exp2(acc[ai][bj][m][1][j] * nr)) * pv[4 + j]; }
;                     *(u32x4*)(O + ro + bj * HALF) = pack8(t0, t1); } }
	v_add_f32_e32 v112, 1.0, v112
	v_add_f32_e32 v117, 1.0, v117
	v_add_f32_e32 v113, 1.0, v113
	v_add_f32_e32 v118, 1.0, v118
	v_add_f32_e32 v114, 1.0, v114
	v_add_f32_e32 v119, 1.0, v119
	v_add_f32_e32 v115, 1.0, v115
	v_rcp_f32_e32 v116, v116
	v_rcp_f32_e32 v112, v112
	v_rcp_f32_e32 v117, v117
	v_rcp_f32_e32 v113, v113
	v_rcp_f32_e32 v118, v118
	v_rcp_f32_e32 v114, v114
	v_rcp_f32_e32 v119, v119
	v_rcp_f32_e32 v115, v115
	v_or_b32_e32 v124, 16, v144
	v_ashrrev_i32_e32 v125, 31, v124
	v_lshlrev_b64 v[124:125], 11, v[124:125]
	v_lshl_add_u64 v[124:125], v[124:125], 0, v[146:147]
	v_lshlrev_b64 v[124:125], 1, v[124:125]
	v_lshl_add_u64 v[126:127], s[20:21], 0, v[124:125]
	v_lshlrev_b32_e32 v145, 16, v220
	v_and_b32_e32 v120, 0xffff0000, v220
	v_lshlrev_b32_e32 v154, 16, v221
	v_and_b32_e32 v121, 0xffff0000, v221
	v_lshlrev_b32_e32 v155, 16, v222
	v_and_b32_e32 v122, 0xffff0000, v222
	v_lshlrev_b32_e32 v156, 16, v223
	v_and_b32_e32 v123, 0xffff0000, v223
	v_mul_f32_e32 v116, v116, v145
	v_mul_f32_e32 v145, v112, v155
	v_mul_f32_e32 v112, v117, v120
	v_mul_f32_e32 v117, v113, v122
	v_mul_f32_e32 v113, v118, v154
	v_mul_f32_e32 v118, v114, v156
	v_mul_f32_e32 v114, v119, v121
	v_mul_f32_e32 v115, v115, v123
	v_cvt_pk_bf16_f32 v112, v116, v112
	v_cvt_pk_bf16_f32 v113, v113, v114
	v_cvt_pk_bf16_f32 v114, v145, v117
	v_cvt_pk_bf16_f32 v115, v118, v115
	global_store_dwordx4 v[162:163], v[112:115], off offset:256
	global_load_dword v118, v[140:141], off offset:64
	s_nop 0
	global_load_dwordx4 v[112:115], v[126:127], off
	global_load_dwordx4 v[224:227], v[126:127], off offset:256
	v_lshl_add_u64 v[116:117], s[24:25], 0, v[124:125]
	s_waitcnt vmcnt(0)
	v_mul_f32_e32 v118, 0xbfb8aa3b, v118
	v_mul_f32_e32 v108, v108, v118
	v_mul_f32_e32 v104, v104, v118
	v_mul_f32_e32 v109, v109, v118
	v_mul_f32_e32 v105, v105, v118
	v_mul_f32_e32 v110, v110, v118
	v_mul_f32_e32 v106, v106, v118
	v_mul_f32_e32 v111, v111, v118
	v_mul_f32_e32 v107, v107, v118
	v_exp_f32_e32 v108, v108
	v_exp_f32_e32 v104, v104
	v_exp_f32_e32 v109, v109
	v_exp_f32_e32 v105, v105
	v_exp_f32_e32 v110, v110
	v_exp_f32_e32 v106, v106
	v_exp_f32_e32 v111, v111
	v_exp_f32_e32 v107, v107
	v_add_f32_e32 v108, 1.0, v108
	v_add_f32_e32 v104, 1.0, v104
	v_add_f32_e32 v109, 1.0, v109
	v_add_f32_e32 v105, 1.0, v105
	v_add_f32_e32 v110, 1.0, v110
	v_add_f32_e32 v106, 1.0, v106
	v_add_f32_e32 v111, 1.0, v111
	v_add_f32_e32 v107, 1.0, v107
	v_rcp_f32_e32 v108, v108
	v_rcp_f32_e32 v104, v104
	v_rcp_f32_e32 v109, v109
	v_rcp_f32_e32 v105, v105
	v_rcp_f32_e32 v110, v110
	v_rcp_f32_e32 v106, v106
	v_rcp_f32_e32 v111, v111
	v_rcp_f32_e32 v107, v107
	v_lshlrev_b32_e32 v119, 16, v112
	v_and_b32_e32 v112, 0xffff0000, v112
	v_lshlrev_b32_e32 v120, 16, v113
	v_and_b32_e32 v113, 0xffff0000, v113
	v_lshlrev_b32_e32 v121, 16, v114
	v_and_b32_e32 v114, 0xffff0000, v114
	v_lshlrev_b32_e32 v122, 16, v115
	v_and_b32_e32 v115, 0xffff0000, v115
	v_mul_f32_e32 v108, v108, v119
	v_mul_f32_e32 v119, v104, v121
	v_mul_f32_e32 v104, v109, v112
	v_mul_f32_e32 v109, v105, v114
	v_mul_f32_e32 v105, v110, v120
	v_mul_f32_e32 v110, v106, v122
	v_mul_f32_e32 v106, v111, v113
	v_mul_f32_e32 v107, v107, v115
	v_cvt_pk_bf16_f32 v104, v108, v104
	v_cvt_pk_bf16_f32 v105, v105, v106
	v_cvt_pk_bf16_f32 v106, v119, v109
	v_cvt_pk_bf16_f32 v107, v110, v107
	global_store_dwordx4 v[116:117], v[104:107], off
	v_mul_f32_e32 v100, v100, v118
	v_mul_f32_e32 v96, v96, v118
	v_mul_f32_e32 v101, v101, v118
	v_mul_f32_e32 v97, v97, v118
	v_mul_f32_e32 v102, v102, v118
	v_mul_f32_e32 v98, v98, v118
	v_mul_f32_e32 v103, v103, v118
	v_mul_f32_e32 v99, v99, v118
	v_exp_f32_e32 v100, v100
	v_exp_f32_e32 v96, v96
	v_exp_f32_e32 v101, v101
	v_exp_f32_e32 v97, v97
	v_exp_f32_e32 v102, v102
	v_exp_f32_e32 v98, v98
	v_exp_f32_e32 v103, v103
	v_exp_f32_e32 v99, v99
	v_add_f32_e32 v100, 1.0, v100
	v_add_f32_e32 v96, 1.0, v96
	v_add_f32_e32 v101, 1.0, v101
	v_add_f32_e32 v97, 1.0, v97
	v_add_f32_e32 v102, 1.0, v102
	v_add_f32_e32 v98, 1.0, v98
	v_add_f32_e32 v103, 1.0, v103
	v_add_f32_e32 v99, 1.0, v99
	v_rcp_f32_e32 v100, v100
	v_rcp_f32_e32 v96, v96
	v_rcp_f32_e32 v101, v101
	v_rcp_f32_e32 v97, v97
	v_rcp_f32_e32 v102, v102
	v_rcp_f32_e32 v98, v98
	v_rcp_f32_e32 v103, v103
	v_rcp_f32_e32 v99, v99
	v_or_b32_e32 v108, 32, v144
	v_ashrrev_i32_e32 v109, 31, v108
	v_lshlrev_b64 v[108:109], 11, v[108:109]
	v_lshl_add_u64 v[108:109], v[108:109], 0, v[146:147]
	v_lshlrev_b64 v[108:109], 1, v[108:109]
	v_lshl_add_u64 v[110:111], s[20:21], 0, v[108:109]
	v_lshlrev_b32_e32 v112, 16, v224
	v_and_b32_e32 v104, 0xffff0000, v224
	v_lshlrev_b32_e32 v113, 16, v225
	v_and_b32_e32 v105, 0xffff0000, v225
	v_lshlrev_b32_e32 v114, 16, v226
	v_and_b32_e32 v106, 0xffff0000, v226
	v_lshlrev_b32_e32 v115, 16, v227
	v_and_b32_e32 v107, 0xffff0000, v227
	v_mul_f32_e32 v100, v100, v112
	v_mul_f32_e32 v112, v96, v114
	v_mul_f32_e32 v96, v101, v104
	v_mul_f32_e32 v101, v97, v106
	v_mul_f32_e32 v97, v102, v113
	v_mul_f32_e32 v102, v98, v115
	v_mul_f32_e32 v98, v103, v105
	v_mul_f32_e32 v99, v99, v107
	v_cvt_pk_bf16_f32 v96, v100, v96
	v_cvt_pk_bf16_f32 v97, v97, v98
	v_cvt_pk_bf16_f32 v98, v112, v101
	v_cvt_pk_bf16_f32 v99, v102, v99
	global_store_dwordx4 v[116:117], v[96:99], off offset:256
	global_load_dword v102, v[140:141], off offset:128
	s_nop 0
	global_load_dwordx4 v[96:99], v[110:111], off
	global_load_dwordx4 v[220:223], v[110:111], off offset:256
	v_lshl_add_u64 v[100:101], s[24:25], 0, v[108:109]
	s_waitcnt vmcnt(0)
; __device__ __forceinline__ float bf_lo(unsigned w) { return __uint_as_float(w << 16); }
; __device__ __forceinline__ float bf_hi(unsigned w) { return __uint_as_float(w & 0xffff0000u); }
; __device__ __forceinline__ float fast_rcp(float x) { return __builtin_amdgcn_rcpf(x); }
; __device__ __forceinline__ float fast_exp2(float x) { return __builtin_amdgcn_exp2f(x); }
; __device__ __forceinline__ u32x4 pack8(f32x4 v0, f32x4 v1) { u32x4 w; w.x = cvt_pk_bf16(v0[0], v0[1]); w.y = cvt_pk_bf16(v0[2], v0[3]); w.z = cvt_pk_bf16(v1[0], v1[1]); w.w = cvt_pk_bf16(v1[2], v1[3]); return w; }
;     __device__ __forceinline__ void operator()(const f32x4 (&acc)[2][2][4][2], const Unit& u, int wr, int wc, int fr, int fq) const {
;     ...
;             for (int m = 0; m < 4; ++m) { const size_t ro = (size_t)(row0 + ai * HALF + m * 16) * DM + col0; const float nr = -LOG2E * rs[row0 + ai * HALF + m * 16];
; #pragma unroll
;                 for (int bj = 0; bj < 2; ++bj) {
;                     const u32x4 pw = *(const u32x4*)(PP + ro + bj * HALF);
;                     const float pv[8] = {bf_lo(pw.x), bf_hi(pw.x), bf_lo(pw.y), bf_hi(pw.y), bf_lo(pw.z), bf_hi(pw.z), bf_lo(pw.w), bf_hi(pw.w)};
;                     f32x4 t0, t1;
; #pragma unroll
;                     for (int j = 0; j < 4; ++j) {
;                         t0[j] = fast_rcp(1.0f + fast_exp2(acc[ai][bj][m][0][j] * nr)) * pv[j];
;                         t1[j] = fast_rcp(1.0f + fast_exp2(acc[ai][bj][m][1][j] * nr)) * pv[4 + j]; }
;                     *(u32x4*)(O + ro + bj * HALF) = pack8(t0, t1); } }
	v_mul_f32_e32 v102, 0xbfb8aa3b, v102
	v_mul_f32_e32 v92, v92, v102
	v_mul_f32_e32 v88, v88, v102
	v_mul_f32_e32 v93, v93, v102
	v_mul_f32_e32 v89, v89, v102
	v_mul_f32_e32 v94, v94, v102
	v_mul_f32_e32 v90, v90, v102
	v_mul_f32_e32 v95, v95, v102
	v_mul_f32_e32 v91, v91, v102
	v_exp_f32_e32 v92, v92
	v_exp_f32_e32 v88, v88
	v_exp_f32_e32 v93, v93
	v_exp_f32_e32 v89, v89
	v_exp_f32_e32 v94, v94
	v_exp_f32_e32 v90, v90
	v_exp_f32_e32 v95, v95
	v_exp_f32_e32 v91, v91
	v_add_f32_e32 v92, 1.0, v92
	v_add_f32_e32 v88, 1.0, v88
	v_add_f32_e32 v93, 1.0, v93
	v_add_f32_e32 v89, 1.0, v89
	v_add_f32_e32 v94, 1.0, v94
	v_add_f32_e32 v90, 1.0, v90
	v_add_f32_e32 v95, 1.0, v95
	v_add_f32_e32 v91, 1.0, v91
	v_rcp_f32_e32 v92, v92
	v_rcp_f32_e32 v88, v88
	v_rcp_f32_e32 v93, v93
	v_rcp_f32_e32 v89, v89
	v_rcp_f32_e32 v94, v94
	v_rcp_f32_e32 v90, v90
	v_rcp_f32_e32 v95, v95
	v_rcp_f32_e32 v91, v91
	v_lshlrev_b32_e32 v103, 16, v96
	v_and_b32_e32 v96, 0xffff0000, v96
	v_lshlrev_b32_e32 v104, 16, v97
	v_and_b32_e32 v97, 0xffff0000, v97
	v_lshlrev_b32_e32 v105, 16, v98
	v_and_b32_e32 v98, 0xffff0000, v98
	v_lshlrev_b32_e32 v106, 16, v99
	v_and_b32_e32 v99, 0xffff0000, v99
	v_mul_f32_e32 v92, v92, v103
	v_mul_f32_e32 v103, v88, v105
	v_mul_f32_e32 v88, v93, v96
	v_mul_f32_e32 v93, v89, v98
	v_mul_f32_e32 v89, v94, v104
	v_mul_f32_e32 v94, v90, v106
	v_mul_f32_e32 v90, v95, v97
	v_mul_f32_e32 v91, v91, v99
	v_cvt_pk_bf16_f32 v88, v92, v88
	v_cvt_pk_bf16_f32 v89, v89, v90
	v_cvt_pk_bf16_f32 v90, v103, v93
	v_cvt_pk_bf16_f32 v91, v94, v91
	global_store_dwordx4 v[100:101], v[88:91], off
	v_mul_f32_e32 v84, v84, v102
	v_mul_f32_e32 v80, v80, v102
	v_mul_f32_e32 v85, v85, v102
	v_mul_f32_e32 v81, v81, v102
	v_mul_f32_e32 v86, v86, v102
	v_mul_f32_e32 v82, v82, v102
	v_mul_f32_e32 v87, v87, v102
	v_mul_f32_e32 v83, v83, v102
	v_exp_f32_e32 v84, v84
	v_exp_f32_e32 v80, v80
	v_exp_f32_e32 v85, v85
	v_exp_f32_e32 v81, v81
	v_exp_f32_e32 v86, v86
	v_exp_f32_e32 v82, v82
	v_exp_f32_e32 v87, v87
	v_exp_f32_e32 v83, v83
	v_add_f32_e32 v84, 1.0, v84
	v_add_f32_e32 v80, 1.0, v80
	v_add_f32_e32 v85, 1.0, v85
	v_add_f32_e32 v81, 1.0, v81
	v_add_f32_e32 v86, 1.0, v86
	v_add_f32_e32 v82, 1.0, v82
	v_add_f32_e32 v87, 1.0, v87
	v_add_f32_e32 v83, 1.0, v83
	v_rcp_f32_e32 v84, v84
	v_rcp_f32_e32 v80, v80
	v_rcp_f32_e32 v85, v85
	v_rcp_f32_e32 v81, v81
	v_rcp_f32_e32 v86, v86
	v_rcp_f32_e32 v82, v82
	v_rcp_f32_e32 v87, v87
	v_rcp_f32_e32 v83, v83
	v_or_b32_e32 v92, 48, v144
	v_ashrrev_i32_e32 v93, 31, v92
	v_lshlrev_b64 v[92:93], 11, v[92:93]
	v_lshl_add_u64 v[92:93], v[92:93], 0, v[146:147]
	v_lshlrev_b64 v[92:93], 1, v[92:93]
	v_lshl_add_u64 v[94:95], s[20:21], 0, v[92:93]
	v_lshlrev_b32_e32 v96, 16, v220
	v_and_b32_e32 v88, 0xffff0000, v220
	v_lshlrev_b32_e32 v97, 16, v221
	v_and_b32_e32 v89, 0xffff0000, v221
	v_lshlrev_b32_e32 v98, 16, v222
	v_and_b32_e32 v90, 0xffff0000, v222
	v_lshlrev_b32_e32 v99, 16, v223
	v_and_b32_e32 v91, 0xffff0000, v223
	v_mul_f32_e32 v84, v84, v96
	v_mul_f32_e32 v96, v80, v98
	v_mul_f32_e32 v80, v85, v88
	v_mul_f32_e32 v85, v81, v90
	v_mul_f32_e32 v81, v86, v97
	v_mul_f32_e32 v86, v82, v99
	v_mul_f32_e32 v82, v87, v89
	v_mul_f32_e32 v83, v83, v91
	v_cvt_pk_bf16_f32 v80, v84, v80
	v_cvt_pk_bf16_f32 v81, v81, v82
	v_cvt_pk_bf16_f32 v82, v96, v85
	v_cvt_pk_bf16_f32 v83, v86, v83
	global_store_dwordx4 v[100:101], v[80:83], off offset:256
	global_load_dword v86, v[140:141], off offset:192
	s_nop 0
	global_load_dwordx4 v[80:83], v[94:95], off
	global_load_dwordx4 v[224:227], v[94:95], off offset:256
	v_lshl_add_u64 v[84:85], s[24:25], 0, v[92:93]
	s_waitcnt vmcnt(0)
	v_mul_f32_e32 v86, 0xbfb8aa3b, v86
	v_mul_f32_e32 v76, v76, v86
	v_mul_f32_e32 v72, v72, v86
	v_mul_f32_e32 v77, v77, v86
	v_mul_f32_e32 v73, v73, v86
	v_mul_f32_e32 v78, v78, v86
	v_mul_f32_e32 v74, v74, v86
	v_mul_f32_e32 v79, v79, v86
	v_mul_f32_e32 v75, v75, v86
	v_exp_f32_e32 v76, v76
	v_exp_f32_e32 v72, v72
	v_exp_f32_e32 v77, v77
	v_exp_f32_e32 v73, v73
	v_exp_f32_e32 v78, v78
	v_exp_f32_e32 v74, v74
	v_exp_f32_e32 v79, v79
	v_exp_f32_e32 v75, v75
	v_add_f32_e32 v76, 1.0, v76
	v_add_f32_e32 v72, 1.0, v72
	v_add_f32_e32 v77, 1.0, v77
	v_add_f32_e32 v73, 1.0, v73
	v_add_f32_e32 v78, 1.0, v78
	v_add_f32_e32 v74, 1.0, v74
	v_add_f32_e32 v79, 1.0, v79
	v_add_f32_e32 v75, 1.0, v75
	v_rcp_f32_e32 v76, v76
	v_rcp_f32_e32 v72, v72
	v_rcp_f32_e32 v77, v77
	v_rcp_f32_e32 v73, v73
	v_rcp_f32_e32 v78, v78
	v_rcp_f32_e32 v74, v74
	v_rcp_f32_e32 v79, v79
	v_rcp_f32_e32 v75, v75
	v_lshlrev_b32_e32 v87, 16, v80
	v_and_b32_e32 v80, 0xffff0000, v80
	v_lshlrev_b32_e32 v88, 16, v81
	v_and_b32_e32 v81, 0xffff0000, v81
	v_lshlrev_b32_e32 v89, 16, v82
	v_and_b32_e32 v82, 0xffff0000, v82
	v_lshlrev_b32_e32 v90, 16, v83
	v_and_b32_e32 v83, 0xffff0000, v83
	v_mul_f32_e32 v76, v76, v87
	v_mul_f32_e32 v87, v72, v89
	v_mul_f32_e32 v72, v77, v80
	v_mul_f32_e32 v77, v73, v82
	v_mul_f32_e32 v73, v78, v88
	v_mul_f32_e32 v78, v74, v90
	v_mul_f32_e32 v74, v79, v81
	v_mul_f32_e32 v75, v75, v83
	v_cvt_pk_bf16_f32 v72, v76, v72
	v_cvt_pk_bf16_f32 v73, v73, v74
	v_cvt_pk_bf16_f32 v74, v87, v77
	v_cvt_pk_bf16_f32 v75, v78, v75
	global_store_dwordx4 v[84:85], v[72:75], off
	v_mul_f32_e32 v68, v68, v86
	v_mul_f32_e32 v64, v64, v86
	v_mul_f32_e32 v69, v69, v86
	v_mul_f32_e32 v65, v65, v86
	v_mul_f32_e32 v70, v70, v86
	v_mul_f32_e32 v66, v66, v86
	v_mul_f32_e32 v71, v71, v86
	v_mul_f32_e32 v67, v67, v86
	v_exp_f32_e32 v68, v68
	v_exp_f32_e32 v64, v64
	v_exp_f32_e32 v69, v69
	v_exp_f32_e32 v65, v65
	v_exp_f32_e32 v70, v70
	v_exp_f32_e32 v66, v66
	v_exp_f32_e32 v71, v71
	v_exp_f32_e32 v67, v67
	v_add_f32_e32 v68, 1.0, v68
; __device__ __forceinline__ float bf_lo(unsigned w) { return __uint_as_float(w << 16); }
; __device__ __forceinline__ float bf_hi(unsigned w) { return __uint_as_float(w & 0xffff0000u); }
; __device__ __forceinline__ float fast_rcp(float x) { return __builtin_amdgcn_rcpf(x); }
; __device__ __forceinline__ float fast_exp2(float x) { return __builtin_amdgcn_exp2f(x); }
; __device__ __forceinline__ u32x4 pack8(f32x4 v0, f32x4 v1) { u32x4 w; w.x = cvt_pk_bf16(v0[0], v0[1]); w.y = cvt_pk_bf16(v0[2], v0[3]); w.z = cvt_pk_bf16(v1[0], v1[1]); w.w = cvt_pk_bf16(v1[2], v1[3]); return w; }
;     __device__ __forceinline__ void operator()(const f32x4 (&acc)[2][2][4][2], const Unit& u, int wr, int wc, int fr, int fq) const {
;     ...
;             for (int m = 0; m < 4; ++m) { const size_t ro = (size_t)(row0 + ai * HALF + m * 16) * DM + col0; const float nr = -LOG2E * rs[row0 + ai * HALF + m * 16];
; #pragma unroll
;                 for (int bj = 0; bj < 2; ++bj) {
;                     const u32x4 pw = *(const u32x4*)(PP + ro + bj * HALF);
;                     const float pv[8] = {bf_lo(pw.x), bf_hi(pw.x), bf_lo(pw.y), bf_hi(pw.y), bf_lo(pw.z), bf_hi(pw.z), bf_lo(pw.w), bf_hi(pw.w)};
;                     f32x4 t0, t1;
; #pragma unroll
;                     for (int j = 0; j < 4; ++j) {
;                         t0[j] = fast_rcp(1.0f + fast_exp2(acc[ai][bj][m][0][j] * nr)) * pv[j];
;                         t1[j] = fast_rcp(1.0f + fast_exp2(acc[ai][bj][m][1][j] * nr)) * pv[4 + j]; }
;                     *(u32x4*)(O + ro + bj * HALF) = pack8(t0, t1); } }
	v_add_f32_e32 v64, 1.0, v64
	v_add_f32_e32 v69, 1.0, v69
	v_add_f32_e32 v65, 1.0, v65
	v_add_f32_e32 v70, 1.0, v70
	v_add_f32_e32 v66, 1.0, v66
	v_add_f32_e32 v71, 1.0, v71
	v_add_f32_e32 v67, 1.0, v67
	v_rcp_f32_e32 v68, v68
	v_rcp_f32_e32 v64, v64
	v_rcp_f32_e32 v69, v69
	v_rcp_f32_e32 v65, v65
	v_rcp_f32_e32 v70, v70
	v_rcp_f32_e32 v66, v66
	v_rcp_f32_e32 v71, v71
	v_rcp_f32_e32 v67, v67
	v_lshl_add_u64 v[76:77], v[142:143], 0, s[2:3]
	v_lshl_add_u64 v[78:79], s[20:21], 0, v[76:77]
	v_lshlrev_b32_e32 v80, 16, v224
	v_and_b32_e32 v72, 0xffff0000, v224
	v_lshlrev_b32_e32 v81, 16, v225
	v_and_b32_e32 v73, 0xffff0000, v225
	v_lshlrev_b32_e32 v82, 16, v226
	v_and_b32_e32 v74, 0xffff0000, v226
	v_lshlrev_b32_e32 v83, 16, v227
	v_and_b32_e32 v75, 0xffff0000, v227
	v_mul_f32_e32 v68, v68, v80
	v_mul_f32_e32 v80, v64, v82
	v_mul_f32_e32 v64, v69, v72
	v_mul_f32_e32 v69, v65, v74
	v_mul_f32_e32 v65, v70, v81
	v_mul_f32_e32 v70, v66, v83
	v_mul_f32_e32 v66, v71, v73
	v_mul_f32_e32 v67, v67, v75
	v_cvt_pk_bf16_f32 v64, v68, v64
	v_cvt_pk_bf16_f32 v65, v65, v66
	v_cvt_pk_bf16_f32 v66, v80, v69
	v_cvt_pk_bf16_f32 v67, v70, v67
	global_store_dwordx4 v[84:85], v[64:67], off offset:256
	global_load_dword v70, v[140:141], off offset:512
	s_nop 0
	global_load_dwordx4 v[64:67], v[78:79], off
	global_load_dwordx4 v[220:223], v[78:79], off offset:256
	v_lshl_add_u64 v[68:69], s[24:25], 0, v[76:77]
	s_waitcnt vmcnt(0)
	v_mul_f32_e32 v70, 0xbfb8aa3b, v70
	v_mul_f32_e32 v60, v60, v70
	v_mul_f32_e32 v56, v56, v70
	v_mul_f32_e32 v61, v61, v70
	v_mul_f32_e32 v57, v57, v70
	v_mul_f32_e32 v62, v62, v70
	v_mul_f32_e32 v58, v58, v70
	v_mul_f32_e32 v63, v63, v70
	v_mul_f32_e32 v59, v59, v70
	v_exp_f32_e32 v60, v60
	v_exp_f32_e32 v56, v56
	v_exp_f32_e32 v61, v61
	v_exp_f32_e32 v57, v57
	v_exp_f32_e32 v62, v62
	v_exp_f32_e32 v58, v58
	v_exp_f32_e32 v63, v63
	v_exp_f32_e32 v59, v59
	v_add_f32_e32 v60, 1.0, v60
	v_add_f32_e32 v56, 1.0, v56
	v_add_f32_e32 v61, 1.0, v61
	v_add_f32_e32 v57, 1.0, v57
	v_add_f32_e32 v62, 1.0, v62
	v_add_f32_e32 v58, 1.0, v58
	v_add_f32_e32 v63, 1.0, v63
	v_add_f32_e32 v59, 1.0, v59
	v_rcp_f32_e32 v60, v60
	v_rcp_f32_e32 v56, v56
	v_rcp_f32_e32 v61, v61
	v_rcp_f32_e32 v57, v57
	v_rcp_f32_e32 v62, v62
	v_rcp_f32_e32 v58, v58
	v_rcp_f32_e32 v63, v63
	v_rcp_f32_e32 v59, v59
	v_lshlrev_b32_e32 v71, 16, v64
	v_and_b32_e32 v64, 0xffff0000, v64
	v_lshlrev_b32_e32 v72, 16, v65
	v_and_b32_e32 v65, 0xffff0000, v65
	v_lshlrev_b32_e32 v73, 16, v66
	v_and_b32_e32 v66, 0xffff0000, v66
	v_lshlrev_b32_e32 v74, 16, v67
	v_and_b32_e32 v67, 0xffff0000, v67
	v_mul_f32_e32 v60, v60, v71
	v_mul_f32_e32 v71, v56, v73
	v_mul_f32_e32 v56, v61, v64
	v_mul_f32_e32 v61, v57, v66
	v_mul_f32_e32 v57, v62, v72
	v_mul_f32_e32 v62, v58, v74
	v_mul_f32_e32 v58, v63, v65
	v_mul_f32_e32 v59, v59, v67
	v_cvt_pk_bf16_f32 v56, v60, v56
	v_cvt_pk_bf16_f32 v57, v57, v58
	v_cvt_pk_bf16_f32 v58, v71, v61
	v_cvt_pk_bf16_f32 v59, v62, v59
	global_store_dwordx4 v[68:69], v[56:59], off
	v_mul_f32_e32 v52, v52, v70
	v_mul_f32_e32 v48, v48, v70
	v_mul_f32_e32 v53, v53, v70
	v_mul_f32_e32 v49, v49, v70
	v_mul_f32_e32 v54, v54, v70
	v_mul_f32_e32 v50, v50, v70
	v_mul_f32_e32 v55, v55, v70
	v_mul_f32_e32 v51, v51, v70
	v_exp_f32_e32 v52, v52
	v_exp_f32_e32 v48, v48
	v_exp_f32_e32 v53, v53
	v_exp_f32_e32 v49, v49
	v_exp_f32_e32 v54, v54
	v_exp_f32_e32 v50, v50
	v_exp_f32_e32 v55, v55
	v_exp_f32_e32 v51, v51
	v_add_f32_e32 v52, 1.0, v52
	v_add_f32_e32 v48, 1.0, v48
	v_add_f32_e32 v53, 1.0, v53
	v_add_f32_e32 v49, 1.0, v49
	v_add_f32_e32 v54, 1.0, v54
	v_add_f32_e32 v50, 1.0, v50
	v_add_f32_e32 v55, 1.0, v55
	v_add_f32_e32 v51, 1.0, v51
	v_rcp_f32_e32 v52, v52
	v_rcp_f32_e32 v48, v48
	v_rcp_f32_e32 v53, v53
	v_rcp_f32_e32 v49, v49
	v_rcp_f32_e32 v54, v54
	v_rcp_f32_e32 v50, v50
	v_rcp_f32_e32 v55, v55
	v_rcp_f32_e32 v51, v51
	v_lshl_add_u64 v[60:61], v[142:143], 0, s[6:7]
	v_lshl_add_u64 v[62:63], s[20:21], 0, v[60:61]
	v_lshlrev_b32_e32 v64, 16, v220
	v_and_b32_e32 v56, 0xffff0000, v220
	v_lshlrev_b32_e32 v65, 16, v221
	v_and_b32_e32 v57, 0xffff0000, v221
	v_lshlrev_b32_e32 v66, 16, v222
	v_and_b32_e32 v58, 0xffff0000, v222
	v_lshlrev_b32_e32 v67, 16, v223
	v_and_b32_e32 v59, 0xffff0000, v223
	v_mul_f32_e32 v52, v52, v64
	v_mul_f32_e32 v64, v48, v66
	v_mul_f32_e32 v48, v53, v56
	v_mul_f32_e32 v53, v49, v58
	v_mul_f32_e32 v49, v54, v65
	v_mul_f32_e32 v54, v50, v67
	v_mul_f32_e32 v50, v55, v57
	v_mul_f32_e32 v51, v51, v59
	v_cvt_pk_bf16_f32 v48, v52, v48
	v_cvt_pk_bf16_f32 v49, v49, v50
	v_cvt_pk_bf16_f32 v50, v64, v53
	v_cvt_pk_bf16_f32 v51, v54, v51
	global_store_dwordx4 v[68:69], v[48:51], off offset:256
	global_load_dword v54, v[140:141], off offset:576
	s_nop 0
	global_load_dwordx4 v[48:51], v[62:63], off
	global_load_dwordx4 v[224:227], v[62:63], off offset:256
	v_lshl_add_u64 v[52:53], s[24:25], 0, v[60:61]
	s_waitcnt vmcnt(0)
; __device__ __forceinline__ float bf_lo(unsigned w) { return __uint_as_float(w << 16); }
; __device__ __forceinline__ float bf_hi(unsigned w) { return __uint_as_float(w & 0xffff0000u); }
; __device__ __forceinline__ float fast_rcp(float x) { return __builtin_amdgcn_rcpf(x); }
; __device__ __forceinline__ float fast_exp2(float x) { return __builtin_amdgcn_exp2f(x); }
; __device__ __forceinline__ u32x4 pack8(f32x4 v0, f32x4 v1) { u32x4 w; w.x = cvt_pk_bf16(v0[0], v0[1]); w.y = cvt_pk_bf16(v0[2], v0[3]); w.z = cvt_pk_bf16(v1[0], v1[1]); w.w = cvt_pk_bf16(v1[2], v1[3]); return w; }
;     __device__ __forceinline__ void operator()(const f32x4 (&acc)[2][2][4][2], const Unit& u, int wr, int wc, int fr, int fq) const {
;     ...
;             for (int m = 0; m < 4; ++m) { const size_t ro = (size_t)(row0 + ai * HALF + m * 16) * DM + col0; const float nr = -LOG2E * rs[row0 + ai * HALF + m * 16];
; #pragma unroll
;                 for (int bj = 0; bj < 2; ++bj) {
;                     const u32x4 pw = *(const u32x4*)(PP + ro + bj * HALF);
;                     const float pv[8] = {bf_lo(pw.x), bf_hi(pw.x), bf_lo(pw.y), bf_hi(pw.y), bf_lo(pw.z), bf_hi(pw.z), bf_lo(pw.w), bf_hi(pw.w)};
;                     f32x4 t0, t1;
; #pragma unroll
;                     for (int j = 0; j < 4; ++j) {
;                         t0[j] = fast_rcp(1.0f + fast_exp2(acc[ai][bj][m][0][j] * nr)) * pv[j];
;                         t1[j] = fast_rcp(1.0f + fast_exp2(acc[ai][bj][m][1][j] * nr)) * pv[4 + j]; }
;                     *(u32x4*)(O + ro + bj * HALF) = pack8(t0, t1); } }
	v_mul_f32_e32 v54, 0xbfb8aa3b, v54
	v_mul_f32_e32 v44, v44, v54
	v_mul_f32_e32 v40, v40, v54
	v_mul_f32_e32 v45, v45, v54
	v_mul_f32_e32 v41, v41, v54
	v_mul_f32_e32 v46, v46, v54
	v_mul_f32_e32 v42, v42, v54
	v_mul_f32_e32 v47, v47, v54
	v_mul_f32_e32 v43, v43, v54
	v_exp_f32_e32 v44, v44
	v_exp_f32_e32 v40, v40
	v_exp_f32_e32 v45, v45
	v_exp_f32_e32 v41, v41
	v_exp_f32_e32 v46, v46
	v_exp_f32_e32 v42, v42
	v_exp_f32_e32 v47, v47
	v_exp_f32_e32 v43, v43
	v_add_f32_e32 v44, 1.0, v44
	v_add_f32_e32 v40, 1.0, v40
	v_add_f32_e32 v45, 1.0, v45
	v_add_f32_e32 v41, 1.0, v41
	v_add_f32_e32 v46, 1.0, v46
	v_add_f32_e32 v42, 1.0, v42
	v_add_f32_e32 v47, 1.0, v47
	v_add_f32_e32 v43, 1.0, v43
	v_rcp_f32_e32 v44, v44
	v_rcp_f32_e32 v40, v40
	v_rcp_f32_e32 v45, v45
	v_rcp_f32_e32 v41, v41
	v_rcp_f32_e32 v46, v46
	v_rcp_f32_e32 v42, v42
	v_rcp_f32_e32 v47, v47
	v_rcp_f32_e32 v43, v43
	v_lshlrev_b32_e32 v55, 16, v48
	v_and_b32_e32 v48, 0xffff0000, v48
	v_lshlrev_b32_e32 v56, 16, v49
	v_and_b32_e32 v49, 0xffff0000, v49
	v_lshlrev_b32_e32 v57, 16, v50
	v_and_b32_e32 v50, 0xffff0000, v50
	v_lshlrev_b32_e32 v58, 16, v51
	v_and_b32_e32 v51, 0xffff0000, v51
	v_mul_f32_e32 v44, v44, v55
	v_mul_f32_e32 v55, v40, v57
	v_mul_f32_e32 v40, v45, v48
	v_mul_f32_e32 v45, v41, v50
	v_mul_f32_e32 v41, v46, v56
	v_mul_f32_e32 v46, v42, v58
	v_mul_f32_e32 v42, v47, v49
	v_mul_f32_e32 v43, v43, v51
	v_cvt_pk_bf16_f32 v40, v44, v40
	v_cvt_pk_bf16_f32 v41, v41, v42
	v_cvt_pk_bf16_f32 v42, v55, v45
	v_cvt_pk_bf16_f32 v43, v46, v43
	global_store_dwordx4 v[52:53], v[40:43], off
	v_mul_f32_e32 v36, v36, v54
	v_mul_f32_e32 v32, v32, v54
	v_mul_f32_e32 v37, v37, v54
	v_mul_f32_e32 v33, v33, v54
	v_mul_f32_e32 v38, v38, v54
	v_mul_f32_e32 v34, v34, v54
	v_mul_f32_e32 v39, v39, v54
	v_mul_f32_e32 v35, v35, v54
	v_exp_f32_e32 v36, v36
	v_exp_f32_e32 v32, v32
	v_exp_f32_e32 v37, v37
	v_exp_f32_e32 v33, v33
	v_exp_f32_e32 v38, v38
	v_exp_f32_e32 v34, v34
	v_exp_f32_e32 v39, v39
	v_exp_f32_e32 v35, v35
	v_add_f32_e32 v36, 1.0, v36
	v_add_f32_e32 v32, 1.0, v32
	v_add_f32_e32 v37, 1.0, v37
	v_add_f32_e32 v33, 1.0, v33
	v_add_f32_e32 v38, 1.0, v38
	v_add_f32_e32 v34, 1.0, v34
	v_add_f32_e32 v39, 1.0, v39
	v_add_f32_e32 v35, 1.0, v35
	v_rcp_f32_e32 v36, v36
	v_rcp_f32_e32 v32, v32
	v_rcp_f32_e32 v37, v37
	v_rcp_f32_e32 v33, v33
	v_rcp_f32_e32 v38, v38
	v_rcp_f32_e32 v34, v34
	v_rcp_f32_e32 v39, v39
	v_rcp_f32_e32 v35, v35
	v_lshl_add_u64 v[44:45], v[142:143], 0, s[8:9]
	v_lshl_add_u64 v[46:47], s[20:21], 0, v[44:45]
	v_lshlrev_b32_e32 v48, 16, v224
	v_and_b32_e32 v40, 0xffff0000, v224
	v_lshlrev_b32_e32 v49, 16, v225
	v_and_b32_e32 v41, 0xffff0000, v225
	v_lshlrev_b32_e32 v50, 16, v226
	v_and_b32_e32 v42, 0xffff0000, v226
	v_lshlrev_b32_e32 v51, 16, v227
	v_and_b32_e32 v43, 0xffff0000, v227
	v_mul_f32_e32 v36, v36, v48
	v_mul_f32_e32 v48, v32, v50
	v_mul_f32_e32 v32, v37, v40
	v_mul_f32_e32 v37, v33, v42
	v_mul_f32_e32 v33, v38, v49
	v_mul_f32_e32 v38, v34, v51
	v_mul_f32_e32 v34, v39, v41
	v_mul_f32_e32 v35, v35, v43
	v_cvt_pk_bf16_f32 v32, v36, v32
	v_cvt_pk_bf16_f32 v33, v33, v34
	v_cvt_pk_bf16_f32 v34, v48, v37
	v_cvt_pk_bf16_f32 v35, v38, v35
	global_store_dwordx4 v[52:53], v[32:35], off offset:256
	global_load_dword v38, v[140:141], off offset:640
	s_nop 0
	global_load_dwordx4 v[32:35], v[46:47], off
	global_load_dwordx4 v[220:223], v[46:47], off offset:256
	v_lshl_add_u64 v[36:37], s[24:25], 0, v[44:45]
	s_waitcnt vmcnt(0)
; __device__ __forceinline__ float bf_lo(unsigned w) { return __uint_as_float(w << 16); }
; __device__ __forceinline__ float bf_hi(unsigned w) { return __uint_as_float(w & 0xffff0000u); }
; __device__ __forceinline__ float fast_rcp(float x) { return __builtin_amdgcn_rcpf(x); }
; __device__ __forceinline__ float fast_exp2(float x) { return __builtin_amdgcn_exp2f(x); }
; __device__ __forceinline__ u32x4 pack8(f32x4 v0, f32x4 v1) { u32x4 w; w.x = cvt_pk_bf16(v0[0], v0[1]); w.y = cvt_pk_bf16(v0[2], v0[3]); w.z = cvt_pk_bf16(v1[0], v1[1]); w.w = cvt_pk_bf16(v1[2], v1[3]); return w; }
;     __device__ __forceinline__ void operator()(const f32x4 (&acc)[2][2][4][2], const Unit& u, int wr, int wc, int fr, int fq) const {
;     ...
;             for (int m = 0; m < 4; ++m) { const size_t ro = (size_t)(row0 + ai * HALF + m * 16) * DM + col0; const float nr = -LOG2E * rs[row0 + ai * HALF + m * 16];
; #pragma unroll
;                 for (int bj = 0; bj < 2; ++bj) {
;                     const u32x4 pw = *(const u32x4*)(PP + ro + bj * HALF);
;                     const float pv[8] = {bf_lo(pw.x), bf_hi(pw.x), bf_lo(pw.y), bf_hi(pw.y), bf_lo(pw.z), bf_hi(pw.z), bf_lo(pw.w), bf_hi(pw.w)};
;                     f32x4 t0, t1;
; #pragma unroll
;                     for (int j = 0; j < 4; ++j) {
;                         t0[j] = fast_rcp(1.0f + fast_exp2(acc[ai][bj][m][0][j] * nr)) * pv[j];
;                         t1[j] = fast_rcp(1.0f + fast_exp2(acc[ai][bj][m][1][j] * nr)) * pv[4 + j]; }
;                     *(u32x4*)(O + ro + bj * HALF) = pack8(t0, t1); } }
	v_mul_f32_e32 v38, 0xbfb8aa3b, v38
	v_mul_f32_e32 v28, v28, v38
	v_mul_f32_e32 v24, v24, v38
	v_mul_f32_e32 v29, v29, v38
	v_mul_f32_e32 v25, v25, v38
	v_mul_f32_e32 v30, v30, v38
	v_mul_f32_e32 v26, v26, v38
	v_mul_f32_e32 v31, v31, v38
	v_mul_f32_e32 v27, v27, v38
	v_exp_f32_e32 v28, v28
	v_exp_f32_e32 v24, v24
	v_exp_f32_e32 v29, v29
	v_exp_f32_e32 v25, v25
	v_exp_f32_e32 v30, v30
	v_exp_f32_e32 v26, v26
	v_exp_f32_e32 v31, v31
	v_exp_f32_e32 v27, v27
	v_add_f32_e32 v28, 1.0, v28
	v_add_f32_e32 v24, 1.0, v24
	v_add_f32_e32 v29, 1.0, v29
	v_add_f32_e32 v25, 1.0, v25
	v_add_f32_e32 v30, 1.0, v30
	v_add_f32_e32 v26, 1.0, v26
	v_add_f32_e32 v31, 1.0, v31
	v_add_f32_e32 v27, 1.0, v27
	v_rcp_f32_e32 v28, v28
	v_rcp_f32_e32 v24, v24
	v_rcp_f32_e32 v29, v29
	v_rcp_f32_e32 v25, v25
	v_rcp_f32_e32 v30, v30
	v_rcp_f32_e32 v26, v26
	v_rcp_f32_e32 v31, v31
	v_rcp_f32_e32 v27, v27
	v_lshlrev_b32_e32 v39, 16, v32
	v_and_b32_e32 v32, 0xffff0000, v32
	v_lshlrev_b32_e32 v40, 16, v33
	v_and_b32_e32 v33, 0xffff0000, v33
	v_lshlrev_b32_e32 v41, 16, v34
	v_and_b32_e32 v34, 0xffff0000, v34
	v_lshlrev_b32_e32 v42, 16, v35
	v_and_b32_e32 v35, 0xffff0000, v35
	v_mul_f32_e32 v28, v28, v39
	v_mul_f32_e32 v39, v24, v41
	v_mul_f32_e32 v24, v29, v32
	v_mul_f32_e32 v29, v25, v34
	v_mul_f32_e32 v25, v30, v40
	v_mul_f32_e32 v30, v26, v42
	v_mul_f32_e32 v26, v31, v33
	v_mul_f32_e32 v27, v27, v35
	v_cvt_pk_bf16_f32 v24, v28, v24
	v_cvt_pk_bf16_f32 v25, v25, v26
	v_cvt_pk_bf16_f32 v26, v39, v29
	v_cvt_pk_bf16_f32 v27, v30, v27
	global_store_dwordx4 v[36:37], v[24:27], off
	v_mul_f32_e32 v20, v20, v38
	v_mul_f32_e32 v16, v16, v38
	v_mul_f32_e32 v21, v21, v38
	v_mul_f32_e32 v17, v17, v38
	v_mul_f32_e32 v22, v22, v38
	v_mul_f32_e32 v18, v18, v38
	v_mul_f32_e32 v23, v23, v38
	v_mul_f32_e32 v19, v19, v38
	v_exp_f32_e32 v20, v20
	v_exp_f32_e32 v16, v16
	v_exp_f32_e32 v21, v21
	v_exp_f32_e32 v17, v17
	v_exp_f32_e32 v22, v22
	v_exp_f32_e32 v18, v18
	v_exp_f32_e32 v23, v23
	v_exp_f32_e32 v19, v19
	v_add_f32_e32 v20, 1.0, v20
	v_add_f32_e32 v16, 1.0, v16
	v_add_f32_e32 v21, 1.0, v21
	v_add_f32_e32 v17, 1.0, v17
	v_add_f32_e32 v22, 1.0, v22
	v_add_f32_e32 v18, 1.0, v18
	v_add_f32_e32 v23, 1.0, v23
	v_add_f32_e32 v19, 1.0, v19
	v_rcp_f32_e32 v20, v20
	v_rcp_f32_e32 v16, v16
	v_rcp_f32_e32 v21, v21
	v_rcp_f32_e32 v17, v17
	v_rcp_f32_e32 v22, v22
	v_rcp_f32_e32 v18, v18
	v_rcp_f32_e32 v23, v23
	v_rcp_f32_e32 v19, v19
	v_lshl_add_u64 v[28:29], v[142:143], 0, s[30:31]
	v_lshl_add_u64 v[30:31], s[20:21], 0, v[28:29]
	v_lshlrev_b32_e32 v32, 16, v220
	v_and_b32_e32 v24, 0xffff0000, v220
	v_lshlrev_b32_e32 v33, 16, v221
	v_and_b32_e32 v25, 0xffff0000, v221
	v_lshlrev_b32_e32 v34, 16, v222
	v_and_b32_e32 v26, 0xffff0000, v222
	v_lshlrev_b32_e32 v35, 16, v223
	v_and_b32_e32 v27, 0xffff0000, v223
	v_mul_f32_e32 v20, v20, v32
	v_mul_f32_e32 v32, v16, v34
	v_mul_f32_e32 v16, v21, v24
	v_mul_f32_e32 v21, v17, v26
	v_mul_f32_e32 v17, v22, v33
	v_mul_f32_e32 v22, v18, v35
	v_mul_f32_e32 v18, v23, v25
	v_mul_f32_e32 v19, v19, v27
	v_cvt_pk_bf16_f32 v16, v20, v16
	v_cvt_pk_bf16_f32 v17, v17, v18
	v_cvt_pk_bf16_f32 v18, v32, v21
	v_cvt_pk_bf16_f32 v19, v22, v19
	global_store_dwordx4 v[36:37], v[16:19], off offset:256
	global_load_dword v22, v[140:141], off offset:704
	s_nop 0
	global_load_dwordx4 v[16:19], v[30:31], off
	global_load_dwordx4 v[224:227], v[30:31], off offset:256
	v_lshl_add_u64 v[20:21], s[24:25], 0, v[28:29]
	s_waitcnt vmcnt(0)
	v_mul_f32_e32 v22, 0xbfb8aa3b, v22
	v_mul_f32_e32 v12, v12, v22
	v_mul_f32_e32 v8, v8, v22
	v_mul_f32_e32 v13, v13, v22
	v_mul_f32_e32 v9, v9, v22
	v_mul_f32_e32 v14, v14, v22
	v_mul_f32_e32 v10, v10, v22
	v_mul_f32_e32 v15, v15, v22
	v_mul_f32_e32 v11, v11, v22
	v_exp_f32_e32 v12, v12
	v_exp_f32_e32 v8, v8
	v_exp_f32_e32 v13, v13
	v_exp_f32_e32 v9, v9
	v_exp_f32_e32 v14, v14
	v_exp_f32_e32 v10, v10
	v_exp_f32_e32 v15, v15
	v_exp_f32_e32 v11, v11
	v_add_f32_e32 v12, 1.0, v12
	v_add_f32_e32 v8, 1.0, v8
	v_add_f32_e32 v13, 1.0, v13
	v_add_f32_e32 v9, 1.0, v9
	v_add_f32_e32 v14, 1.0, v14
	v_add_f32_e32 v10, 1.0, v10
	v_add_f32_e32 v15, 1.0, v15
	v_add_f32_e32 v11, 1.0, v11
	v_rcp_f32_e32 v12, v12
	v_rcp_f32_e32 v8, v8
	v_rcp_f32_e32 v13, v13
	v_rcp_f32_e32 v9, v9
	v_rcp_f32_e32 v14, v14
	v_rcp_f32_e32 v10, v10
	v_rcp_f32_e32 v15, v15
	v_rcp_f32_e32 v11, v11
	v_lshlrev_b32_e32 v23, 16, v16
	v_and_b32_e32 v16, 0xffff0000, v16
	v_lshlrev_b32_e32 v24, 16, v17
	v_and_b32_e32 v17, 0xffff0000, v17
	v_lshlrev_b32_e32 v25, 16, v18
	v_and_b32_e32 v18, 0xffff0000, v18
	v_lshlrev_b32_e32 v26, 16, v19
	v_and_b32_e32 v19, 0xffff0000, v19
	v_mul_f32_e32 v12, v12, v23
	v_mul_f32_e32 v23, v8, v25
	v_mul_f32_e32 v8, v13, v16
	v_mul_f32_e32 v13, v9, v18
	v_mul_f32_e32 v9, v14, v24
	v_mul_f32_e32 v14, v10, v26
	v_mul_f32_e32 v10, v15, v17
	v_mul_f32_e32 v11, v11, v19
	v_cvt_pk_bf16_f32 v8, v12, v8
	v_cvt_pk_bf16_f32 v9, v9, v10
	v_cvt_pk_bf16_f32 v10, v23, v13
	v_cvt_pk_bf16_f32 v11, v14, v11
	global_store_dwordx4 v[20:21], v[8:11], off
	v_mul_f32_e32 v4, v4, v22
	v_mul_f32_e32 v0, v0, v22
	v_mul_f32_e32 v5, v5, v22
	v_mul_f32_e32 v1, v1, v22
	v_mul_f32_e32 v6, v6, v22
	v_mul_f32_e32 v2, v2, v22
	v_mul_f32_e32 v7, v7, v22
	v_mul_f32_e32 v3, v3, v22
	v_exp_f32_e32 v4, v4
	v_exp_f32_e32 v0, v0
	v_exp_f32_e32 v5, v5
	v_exp_f32_e32 v1, v1
	v_exp_f32_e32 v6, v6
	v_exp_f32_e32 v2, v2
	v_exp_f32_e32 v7, v7
	v_exp_f32_e32 v3, v3
	v_add_f32_e32 v4, 1.0, v4
	v_add_f32_e32 v0, 1.0, v0
	v_add_f32_e32 v5, 1.0, v5
	v_add_f32_e32 v1, 1.0, v1
	v_add_f32_e32 v6, 1.0, v6
	v_add_f32_e32 v2, 1.0, v2
	v_add_f32_e32 v7, 1.0, v7
	v_add_f32_e32 v3, 1.0, v3
	v_rcp_f32_e32 v4, v4
	v_rcp_f32_e32 v0, v0
	v_rcp_f32_e32 v5, v5
	v_rcp_f32_e32 v1, v1
	v_rcp_f32_e32 v6, v6
	v_rcp_f32_e32 v2, v2
	v_rcp_f32_e32 v7, v7
	v_rcp_f32_e32 v3, v3
	v_lshlrev_b32_e32 v12, 16, v224
	v_and_b32_e32 v8, 0xffff0000, v224
	v_lshlrev_b32_e32 v13, 16, v225
	v_and_b32_e32 v9, 0xffff0000, v225
	v_lshlrev_b32_e32 v14, 16, v226
	v_and_b32_e32 v10, 0xffff0000, v226
	v_lshlrev_b32_e32 v15, 16, v227
	v_and_b32_e32 v11, 0xffff0000, v227
	v_mul_f32_e32 v4, v4, v12
	v_mul_f32_e32 v12, v0, v14
	v_mul_f32_e32 v0, v5, v8
	v_mul_f32_e32 v5, v1, v10
	v_mul_f32_e32 v1, v6, v13
	v_mul_f32_e32 v6, v2, v15
	v_mul_f32_e32 v2, v7, v9
	v_mul_f32_e32 v3, v3, v11
	v_cvt_pk_bf16_f32 v0, v4, v0
	v_cvt_pk_bf16_f32 v1, v1, v2
	v_cvt_pk_bf16_f32 v2, v12, v5
	v_cvt_pk_bf16_f32 v3, v6, v3
	global_store_dwordx4 v[20:21], v[0:3], off offset:256
	s_cbranch_vccz .LBB0_996
	s_waitcnt vmcnt(0)
	s_cmpk_gt_u32 s10, 0xff
	s_cbranch_scc1 .LBB0_1003
	s_barrier
